# SSM scan: at most 15 LDS reads outstanding (counted lgkmcnt stays exact); otherwise same as previous best
# speedup vs baseline: 1.0012x; 1.0012x over previous
.Lscan_loop:
	ds_read2_b32 v[38:39], v1 offset0:8 offset1:9
	ds_read2_b32 v[40:41], v1 offset0:10 offset1:11
	ds_read2_b32 v[42:43], v1 offset0:12 offset1:13
	ds_read2_b32 v[44:45], v1 offset0:14 offset1:15
	ds_read2_b32 v[46:47], v3 offset0:8 offset1:9
	ds_read2_b32 v[48:49], v3 offset0:10 offset1:11
	ds_read2_b32 v[50:51], v3 offset0:12 offset1:13
	s_waitcnt lgkmcnt(7)
	ds_read2_b32 v[52:53], v3 offset0:14 offset1:15
	v_cvt_pk_bf16_f32 v14, v10, v11
	v_pk_mul_f32 v[16:17], v[8:9], v[10:11] op_sel:[0,1]
	global_store_short v[6:7], v14, off
	v_pk_fma_f32 v[18:19], v[4:5], v[10:11], v[16:17] neg_lo:[0,0,1] neg_hi:[0,0,1]
	v_pk_fma_f32 v[10:11], v[4:5], v[10:11], v[16:17] op_sel_hi:[1,0,1]
	global_store_short_d16_hi v[12:13], v14, off
	v_add_f32_e32 v10, v18, v22
	v_add_f32_e32 v11, v11, v30
	v_cvt_pk_bf16_f32 v15, v10, v11
	v_pk_mul_f32 v[16:17], v[8:9], v[10:11] op_sel:[0,1]
	global_store_short v[6:7], v15, off offset:256
	v_pk_fma_f32 v[18:19], v[4:5], v[10:11], v[16:17] neg_lo:[0,0,1] neg_hi:[0,0,1]
	v_pk_fma_f32 v[10:11], v[4:5], v[10:11], v[16:17] op_sel_hi:[1,0,1]
	global_store_short_d16_hi v[12:13], v15, off offset:256
	v_add_f32_e32 v10, v18, v23
	v_add_f32_e32 v11, v11, v31
	v_cvt_pk_bf16_f32 v14, v10, v11
	v_pk_mul_f32 v[16:17], v[8:9], v[10:11] op_sel:[0,1]
	global_store_short v[6:7], v14, off offset:512
	v_pk_fma_f32 v[18:19], v[4:5], v[10:11], v[16:17] neg_lo:[0,0,1] neg_hi:[0,0,1]
	v_pk_fma_f32 v[10:11], v[4:5], v[10:11], v[16:17] op_sel_hi:[1,0,1]
	global_store_short_d16_hi v[12:13], v14, off offset:512
	v_add_f32_e32 v10, v18, v24
	v_add_f32_e32 v11, v11, v32
	v_cvt_pk_bf16_f32 v15, v10, v11
	v_pk_mul_f32 v[16:17], v[8:9], v[10:11] op_sel:[0,1]
	global_store_short v[6:7], v15, off offset:768
	v_pk_fma_f32 v[18:19], v[4:5], v[10:11], v[16:17] neg_lo:[0,0,1] neg_hi:[0,0,1]
	v_pk_fma_f32 v[10:11], v[4:5], v[10:11], v[16:17] op_sel_hi:[1,0,1]
	global_store_short_d16_hi v[12:13], v15, off offset:768
	v_add_f32_e32 v10, v18, v25
	v_add_f32_e32 v11, v11, v33
	v_cvt_pk_bf16_f32 v14, v10, v11
	v_pk_mul_f32 v[16:17], v[8:9], v[10:11] op_sel:[0,1]
	global_store_short v[6:7], v14, off offset:1024
	v_pk_fma_f32 v[18:19], v[4:5], v[10:11], v[16:17] neg_lo:[0,0,1] neg_hi:[0,0,1]
	v_pk_fma_f32 v[10:11], v[4:5], v[10:11], v[16:17] op_sel_hi:[1,0,1]
	global_store_short_d16_hi v[12:13], v14, off offset:1024
	v_add_f32_e32 v10, v18, v26
	v_add_f32_e32 v11, v11, v34
	v_cvt_pk_bf16_f32 v15, v10, v11
	v_pk_mul_f32 v[16:17], v[8:9], v[10:11] op_sel:[0,1]
	global_store_short v[6:7], v15, off offset:1280
	v_pk_fma_f32 v[18:19], v[4:5], v[10:11], v[16:17] neg_lo:[0,0,1] neg_hi:[0,0,1]
	v_pk_fma_f32 v[10:11], v[4:5], v[10:11], v[16:17] op_sel_hi:[1,0,1]
	global_store_short_d16_hi v[12:13], v15, off offset:1280
	v_add_f32_e32 v10, v18, v27
	v_add_f32_e32 v11, v11, v35
	v_cvt_pk_bf16_f32 v14, v10, v11
	v_pk_mul_f32 v[16:17], v[8:9], v[10:11] op_sel:[0,1]
	global_store_short v[6:7], v14, off offset:1536
	v_pk_fma_f32 v[18:19], v[4:5], v[10:11], v[16:17] neg_lo:[0,0,1] neg_hi:[0,0,1]
	v_pk_fma_f32 v[10:11], v[4:5], v[10:11], v[16:17] op_sel_hi:[1,0,1]
	global_store_short_d16_hi v[12:13], v14, off offset:1536
	v_add_f32_e32 v10, v18, v28
	v_add_f32_e32 v11, v11, v36
	v_cvt_pk_bf16_f32 v15, v10, v11
	v_pk_mul_f32 v[16:17], v[8:9], v[10:11] op_sel:[0,1]
	global_store_short v[6:7], v15, off offset:1792
	v_pk_fma_f32 v[18:19], v[4:5], v[10:11], v[16:17] neg_lo:[0,0,1] neg_hi:[0,0,1]
	v_pk_fma_f32 v[10:11], v[4:5], v[10:11], v[16:17] op_sel_hi:[1,0,1]
	global_store_short_d16_hi v[12:13], v15, off offset:1792
	v_add_f32_e32 v10, v18, v29
	v_add_f32_e32 v11, v11, v37
	ds_read2_b32 v[22:23], v1 offset0:16 offset1:17
	ds_read2_b32 v[24:25], v1 offset0:18 offset1:19
	ds_read2_b32 v[26:27], v1 offset0:20 offset1:21
	ds_read2_b32 v[28:29], v1 offset0:22 offset1:23
	ds_read2_b32 v[30:31], v3 offset0:16 offset1:17
	ds_read2_b32 v[32:33], v3 offset0:18 offset1:19
	ds_read2_b32 v[34:35], v3 offset0:20 offset1:21
	s_waitcnt lgkmcnt(7)
	ds_read2_b32 v[36:37], v3 offset0:22 offset1:23
	v_cvt_pk_bf16_f32 v14, v10, v11
	v_pk_mul_f32 v[16:17], v[8:9], v[10:11] op_sel:[0,1]
	global_store_short v[6:7], v14, off offset:2048
	v_pk_fma_f32 v[18:19], v[4:5], v[10:11], v[16:17] neg_lo:[0,0,1] neg_hi:[0,0,1]
	v_pk_fma_f32 v[10:11], v[4:5], v[10:11], v[16:17] op_sel_hi:[1,0,1]
	global_store_short_d16_hi v[12:13], v14, off offset:2048
	v_add_f32_e32 v10, v18, v38
	v_add_f32_e32 v11, v11, v46
	v_cvt_pk_bf16_f32 v15, v10, v11
	v_pk_mul_f32 v[16:17], v[8:9], v[10:11] op_sel:[0,1]
	global_store_short v[6:7], v15, off offset:2304
	v_pk_fma_f32 v[18:19], v[4:5], v[10:11], v[16:17] neg_lo:[0,0,1] neg_hi:[0,0,1]
	v_pk_fma_f32 v[10:11], v[4:5], v[10:11], v[16:17] op_sel_hi:[1,0,1]
	global_store_short_d16_hi v[12:13], v15, off offset:2304
	v_add_f32_e32 v10, v18, v39
	v_add_f32_e32 v11, v11, v47
	v_cvt_pk_bf16_f32 v14, v10, v11
	v_pk_mul_f32 v[16:17], v[8:9], v[10:11] op_sel:[0,1]
	global_store_short v[6:7], v14, off offset:2560
	v_pk_fma_f32 v[18:19], v[4:5], v[10:11], v[16:17] neg_lo:[0,0,1] neg_hi:[0,0,1]
	v_pk_fma_f32 v[10:11], v[4:5], v[10:11], v[16:17] op_sel_hi:[1,0,1]
	global_store_short_d16_hi v[12:13], v14, off offset:2560
	v_add_f32_e32 v10, v18, v40
	v_add_f32_e32 v11, v11, v48
	v_cvt_pk_bf16_f32 v15, v10, v11
	v_pk_mul_f32 v[16:17], v[8:9], v[10:11] op_sel:[0,1]
	global_store_short v[6:7], v15, off offset:2816
	v_pk_fma_f32 v[18:19], v[4:5], v[10:11], v[16:17] neg_lo:[0,0,1] neg_hi:[0,0,1]
	v_pk_fma_f32 v[10:11], v[4:5], v[10:11], v[16:17] op_sel_hi:[1,0,1]
	global_store_short_d16_hi v[12:13], v15, off offset:2816
	v_add_f32_e32 v10, v18, v41
	v_add_f32_e32 v11, v11, v49
	v_cvt_pk_bf16_f32 v14, v10, v11
	v_pk_mul_f32 v[16:17], v[8:9], v[10:11] op_sel:[0,1]
	global_store_short v[6:7], v14, off offset:3072
	v_pk_fma_f32 v[18:19], v[4:5], v[10:11], v[16:17] neg_lo:[0,0,1] neg_hi:[0,0,1]
	v_pk_fma_f32 v[10:11], v[4:5], v[10:11], v[16:17] op_sel_hi:[1,0,1]
	global_store_short_d16_hi v[12:13], v14, off offset:3072
	v_add_f32_e32 v10, v18, v42
	v_add_f32_e32 v11, v11, v50
	v_cvt_pk_bf16_f32 v15, v10, v11
	v_pk_mul_f32 v[16:17], v[8:9], v[10:11] op_sel:[0,1]
	global_store_short v[6:7], v15, off offset:3328
	v_pk_fma_f32 v[18:19], v[4:5], v[10:11], v[16:17] neg_lo:[0,0,1] neg_hi:[0,0,1]
	v_pk_fma_f32 v[10:11], v[4:5], v[10:11], v[16:17] op_sel_hi:[1,0,1]
	global_store_short_d16_hi v[12:13], v15, off offset:3328
	v_add_f32_e32 v10, v18, v43
	v_add_f32_e32 v11, v11, v51
	v_cvt_pk_bf16_f32 v14, v10, v11
	v_pk_mul_f32 v[16:17], v[8:9], v[10:11] op_sel:[0,1]
	global_store_short v[6:7], v14, off offset:3584
	v_pk_fma_f32 v[18:19], v[4:5], v[10:11], v[16:17] neg_lo:[0,0,1] neg_hi:[0,0,1]
	v_pk_fma_f32 v[10:11], v[4:5], v[10:11], v[16:17] op_sel_hi:[1,0,1]
	global_store_short_d16_hi v[12:13], v14, off offset:3584
	v_add_f32_e32 v10, v18, v44
	v_add_f32_e32 v11, v11, v52
	v_cvt_pk_bf16_f32 v15, v10, v11
	v_pk_mul_f32 v[16:17], v[8:9], v[10:11] op_sel:[0,1]
	global_store_short v[6:7], v15, off offset:3840
	v_pk_fma_f32 v[18:19], v[4:5], v[10:11], v[16:17] neg_lo:[0,0,1] neg_hi:[0,0,1]
	v_pk_fma_f32 v[10:11], v[4:5], v[10:11], v[16:17] op_sel_hi:[1,0,1]
	global_store_short_d16_hi v[12:13], v15, off offset:3840
	v_add_f32_e32 v10, v18, v45
	v_add_f32_e32 v11, v11, v53
	v_add_u32_e32 v1, 64, v1
	v_add_u32_e32 v3, 64, v3
	v_lshl_add_u64 v[6:7], v[6:7], 0, s[6:7]
	v_lshl_add_u64 v[12:13], v[12:13], 0, s[6:7]
	s_sub_i32 s8, s8, 1
	s_cmp_lg_u32 s8, 0
	s_cbranch_scc1 .Lscan_loop
	s_waitcnt lgkmcnt(0)
	s_branch .LBB0_534
